# gmlp_item: the four serialized norm-weight loads issued with the item's first load batch into scratch registers (copied at the original sites)
# baseline (speedup 1.0000x reference)
; #define LAS __attribute__((address_space(3)))
; __device__ __forceinline__ float bflo(unsigned w) { return __uint_as_float(w << 16); }
; __device__ __forceinline__ float bfhi(unsigned w) { return __uint_as_float(w & 0xffff0000u); }
; __device__ __forceinline__ float gelu_t(float x) { return x * sigm(1.5957691216057308f * (x + 0.044715f * x * x * x)); }
; __device__ __forceinline__ int opaque_tid() { int t = threadIdx.x; asm volatile("" : "+v"(t)); return t; }
; __device__ __forceinline__ void gmlp_item(const Params& p, int l, int item, LAS unsigned char* lds) {
;     const int tid = opaque_tid(), wid = tid >> 6, lane = tid & 63, fr = lane & 15, fq = lane >> 4;
;     const int b = item >> 6, blk = (item >> 2) & 15, g = item & 3;
;     LAS bf16_t* vnT = (LAS bf16_t*)lds;
;     const size_t T0 = (size_t)b * SEQ + blk * 128;
;     lds_barrier();
;     const int nks = (wid >> 1) + 1;
;     const size_t Tw = T0 + wid * 16 + fr;
;     bf16x8 bwp[4]; u32x2 uwp[4];
;     { const bf16_t* wp = p.gmw + (((size_t)l * 4 + g) * 128 + wid * 16 + fr) * 128 + fq * 8;
; #pragma unroll
;       for (int ks = 0; ks < 4; ++ks) bwp[ks] = *(const bf16x8*)(wp + (ks < nks ? ks : 0) * 32);
; #pragma unroll
;       for (int ct = 0; ct < 4; ++ct) uwp[ct] = *(const u32x2*)(p.z + Tw * ZLD + 1792 + g * 64 + ct * 16 + fq * 4); }
;     const float bsv = p.gm_bs[((size_t)l * 4 + g) * 128 + wid * 16 + fr];
;     { const int pp = tid >> 2, qd = tid & 3; const bf16_t* vp = p.z + (T0 + pp) * ZLD + 2048 + qd * 16;
;       float keep[16]; float ss = 0.f;
; #pragma unroll
;       for (int i = 0; i < 16; ++i) keep[i] = 0.f;
; #pragma unroll
;       for (int gg = 0; gg < 4; ++gg) { const u32x4 w0 = *(const u32x4*)(vp + gg * 64), w1 = *(const u32x4*)(vp + gg * 64 + 8);
;           const float v[16] = {bflo(w0.x), bfhi(w0.x), bflo(w0.y), bfhi(w0.y), bflo(w0.z), bfhi(w0.z), bflo(w0.w), bfhi(w0.w),
;                                bflo(w1.x), bfhi(w1.x), bflo(w1.y), bfhi(w1.y), bflo(w1.z), bfhi(w1.z), bflo(w1.w), bfhi(w1.w)};
; #pragma unroll
;           for (int i = 0; i < 16; ++i) { const float ge = gelu_t(v[i]); ss += ge * ge; keep[i] = (gg == g) ? ge : keep[i]; } }
;       ss += __shfl_xor(ss, 1); ss += __shfl_xor(ss, 2);
;       const float rstd = rsqrtf(ss * (1.f / 256.f) + EPS);
;       const float* ng = p.gm_norm_g + l * 256 + g * 64 + qd * 16;
.LBB0_319:
	s_and_b64 vcc, exec, s[6:7]
	s_cbranch_vccz .LBB0_342
	v_mov_b32_e32 v34, v202
	s_bfe_u32 s37, s72, 0x20003
	s_lshl_b32 s96, s37, 7
	v_ashrrev_i32_e32 v30, 2, v34
	v_and_b32_e32 v32, 15, v34
	v_and_b32_e32 v0, -16, v30
	s_or_b32 s6, s26, s96
	v_ashrrev_i32_e32 v1, 31, v0
	v_or_b32_e32 v4, s6, v32
	v_mov_b32_e32 v5, s27
	v_lshl_add_u64 v[22:23], v[4:5], 0, v[0:1]
	v_bfe_u32 v48, v34, 4, 2
	v_ashrrev_i32_e32 v33, 7, v34
	v_lshlrev_b64 v[4:5], 8, v[22:23]
	v_lshl_add_u64 v[4:5], s[4:5], 0, v[4:5]
	v_lshlrev_b32_e32 v28, 4, v48
	v_mov_b32_e32 v29, v2
	v_cmp_gt_i32_e32 vcc, 1, v33
	v_lshl_add_u64 v[4:5], v[4:5], 0, v[28:29]
	v_mov_b32_e32 v7, v2
	v_cndmask_b32_e64 v6, 64, 0, vcc
	v_mov_b32_e32 v20, s0
	s_add_i32 s0, s21, 0xffffff00
	s_waitcnt lgkmcnt(0)
	s_barrier
	v_lshl_add_u64 v[6:7], v[4:5], 0, v[6:7]
	v_cmp_gt_i32_e32 vcc, 2, v33
	v_mov_b32_e32 v21, s14
	s_ashr_i32 s14, s0, 6
	global_load_dwordx4 v[16:19], v[4:5], off
	global_load_dwordx4 v[12:15], v[6:7], off
	v_cndmask_b32_e64 v6, v243, 0, vcc
	v_mov_b32_e32 v7, v2
	s_ashr_i32 s15, s14, 31
	s_lshl_b32 s0, s16, 5
	v_lshl_add_u64 v[6:7], v[4:5], 0, v[6:7]
	v_cmp_gt_i32_e64 s[8:9], 3, v33
	s_and_b32 s0, s0, 0x780
	global_load_dwordx4 v[8:11], v[6:7], off
	v_cndmask_b32_e64 v6, v254, 0, s[8:9]
	s_lshl_b64 s[8:9], s[14:15], 11
	s_or_b32 s8, s8, s0
	v_lshl_add_u64 v[46:47], s[8:9], 0, v[0:1]
	v_or_b32_e32 v46, v46, v32
	v_mov_b64_e32 v[26:27], s[34:35]
	s_movk_i32 s0, 0x1600
	v_mad_u64_u32 v[0:1], s[14:15], v46, s0, v[26:27]
	v_mad_i32_i24 v1, v47, s0, v1
	v_lshlrev_b32_e32 v24, 3, v48
	v_mov_b32_e32 v25, v2
	v_mov_b32_e32 v7, v2
	v_lshl_add_u64 v[0:1], v[0:1], 0, s[96:97]
	v_lshl_add_u64 v[4:5], v[4:5], 0, v[6:7]
	v_lshl_add_u64 v[0:1], v[0:1], 0, v[24:25]
	v_lshl_add_u64 v[20:21], v[22:23], 2, v[20:21]
	v_ashrrev_i32_e32 v31, 31, v30
	global_load_dwordx4 v[4:7], v[4:5], off
	s_nop 0
	global_load_dwordx2 v[44:45], v[0:1], off offset:3584
	global_load_dwordx2 v[42:43], v[0:1], off offset:3616
	global_load_dwordx2 v[40:41], v[0:1], off offset:3648
	s_nop 0
	global_load_dwordx2 v[0:1], v[0:1], off offset:3680
	s_cmp_eq_u32 s37, 0
	global_load_dword v3, v[20:21], off
	v_lshl_add_u64 v[20:21], s[8:9], 0, v[30:31]
	v_mad_u64_u32 v[22:23], s[8:9], v20, s0, v[26:27]
	v_lshlrev_b32_e32 v20, 4, v34
	v_and_b32_e32 v29, 48, v20
	v_mov_b32_e32 v92, s23
	v_mov_b32_e32 v93, s36
	v_mov_b32_e32 v94, s28
	v_mov_b32_e32 v95, s29
	v_lshl_add_u64 v[92:93], v[94:95], 2, v[92:93]
	s_mul_i32 s98, s37, 0x100
	v_lshl_add_u32 v94, v29, 2, s98
	v_mov_b32_e32 v95, 0
	v_lshl_add_u64 v[90:91], v[92:93], 0, v[94:95]
	global_load_dwordx4 v[74:77], v[90:91], off
	global_load_dwordx4 v[78:81], v[90:91], off offset:16
	global_load_dwordx4 v[82:85], v[90:91], off offset:32
	global_load_dwordx4 v[86:89], v[90:91], off offset:48
	v_mad_i32_i24 v23, v21, s0, v23
	v_lshlrev_b32_e32 v20, 1, v29
	v_mov_b32_e32 v21, v2
	v_lshl_add_u64 v[20:21], v[22:23], 0, v[20:21]
	s_mov_b64 s[8:9], 0x1000
	v_lshl_add_u64 v[24:25], v[20:21], 0, s[8:9]
	v_add_co_u32_e64 v20, s[8:9], s80, v20
	v_lshlrev_b32_e32 v30, 1, v30
	s_nop 0
	v_addc_co_u32_e64 v21, s[8:9], 0, v21, s[8:9]
	global_load_dwordx4 v[20:23], v[20:21], off
	s_nop 0
	global_load_dwordx4 v[34:37], v[24:25], off offset:16
	global_load_dwordx4 v[102:105], v[24:25], off offset:144
	global_load_dwordx4 v[106:109], v[24:25], off offset:128
	global_load_dwordx4 v[110:113], v[24:25], off offset:272
	global_load_dwordx4 v[114:117], v[24:25], off offset:256
	global_load_dwordx4 v[118:121], v[24:25], off offset:400
	global_load_dwordx4 v[122:125], v[24:25], off offset:384
	s_cselect_b64 s[8:9], -1, 0
	s_cmp_eq_u32 s37, 1
	v_cmp_lt_i32_e64 s[6:7], 0, v33
	v_cmp_lt_i32_e64 s[4:5], 1, v33
	v_cmp_lt_i32_e32 vcc, 2, v33
	s_waitcnt vmcnt(7)
	v_lshlrev_b32_e32 v26, 16, v20
	v_mul_f32_e32 v31, 0x3d372713, v26
	v_mul_f32_e32 v31, v31, v26
	v_fma_f32 v31, v31, v26, v26
	v_mul_f32_e32 v31, 0x3fcc422a, v31
	v_mul_f32_e32 v31, 0xbfb8aa3b, v31
	v_exp_f32_e32 v31, v31
	v_and_b32_e32 v20, 0xffff0000, v20
	v_lshlrev_b32_e32 v27, 16, v21
	v_and_b32_e32 v21, 0xffff0000, v21
	v_add_f32_e32 v31, 1.0, v31
	v_rcp_f32_e32 v31, v31
	v_lshlrev_b32_e32 v38, 16, v22
	v_and_b32_e32 v22, 0xffff0000, v22
	v_lshlrev_b32_e32 v39, 16, v23
	v_mul_f32_e32 v26, v31, v26
	v_mul_f32_e32 v31, 0x3d372713, v20
	v_mul_f32_e32 v31, v31, v20
	v_fma_f32 v31, v31, v20, v20
	v_mul_f32_e32 v31, 0x3fcc422a, v31
	v_mul_f32_e32 v31, 0xbfb8aa3b, v31
	v_exp_f32_e32 v31, v31
	v_cndmask_b32_e64 v53, 0, v26, s[8:9]
	v_and_b32_e32 v23, 0xffff0000, v23
	s_waitcnt vmcnt(6)
; __device__ __forceinline__ float bflo(unsigned w) { return __uint_as_float(w << 16); }
; __device__ __forceinline__ float bfhi(unsigned w) { return __uint_as_float(w & 0xffff0000u); }
; __device__ __forceinline__ float gelu_t(float x) { return x * sigm(1.5957691216057308f * (x + 0.044715f * x * x * x)); }
; __device__ __forceinline__ void gmlp_item(const Params& p, int l, int item, LAS unsigned char* lds) {
;     ...
; #pragma unroll
;       for (int i = 0; i < 16; ++i) keep[i] = 0.f;
; #pragma unroll
;       for (int gg = 0; gg < 4; ++gg) { const u32x4 w0 = *(const u32x4*)(vp + gg * 64), w1 = *(const u32x4*)(vp + gg * 64 + 8);
;           const float v[16] = {bflo(w0.x), bfhi(w0.x), bflo(w0.y), bfhi(w0.y), bflo(w0.z), bfhi(w0.z), bflo(w0.w), bfhi(w0.w),
;                                bflo(w1.x), bfhi(w1.x), bflo(w1.y), bfhi(w1.y), bflo(w1.z), bfhi(w1.z), bflo(w1.w), bfhi(w1.w)};
; #pragma unroll
;           for (int i = 0; i < 16; ++i) { const float ge = gelu_t(v[i]); ss += ge * ge; keep[i] = (gg == g) ? ge : keep[i]; } }
	v_lshlrev_b32_e32 v49, 16, v34
	v_add_f32_e32 v31, 1.0, v31
	v_rcp_f32_e32 v31, v31
	v_and_b32_e32 v34, 0xffff0000, v34
	v_lshlrev_b32_e32 v50, 16, v35
	v_and_b32_e32 v35, 0xffff0000, v35
	v_mul_f32_e32 v20, v31, v20
	v_mul_f32_e32 v31, v20, v20
	v_fmac_f32_e32 v31, v26, v26
	v_cndmask_b32_e64 v26, 0, v20, s[8:9]
	v_mul_f32_e32 v20, 0x3d372713, v27
	v_mul_f32_e32 v20, v20, v27
	v_fma_f32 v20, v20, v27, v27
	v_mul_f32_e32 v20, 0x3fcc422a, v20
	v_mul_f32_e32 v20, 0xbfb8aa3b, v20
	v_exp_f32_e32 v20, v20
	v_lshlrev_b32_e32 v51, 16, v36
	v_and_b32_e32 v36, 0xffff0000, v36
	v_lshlrev_b32_e32 v52, 16, v37
	v_add_f32_e32 v20, 1.0, v20
	v_rcp_f32_e32 v20, v20
	v_and_b32_e32 v37, 0xffff0000, v37
	v_mul_f32_e32 v20, v20, v27
	v_fmac_f32_e32 v31, v20, v20
	v_cndmask_b32_e64 v27, 0, v20, s[8:9]
	v_mul_f32_e32 v20, 0x3d372713, v21
	v_mul_f32_e32 v20, v20, v21
	v_fma_f32 v20, v20, v21, v21
	v_mul_f32_e32 v20, 0x3fcc422a, v20
	v_mul_f32_e32 v20, 0xbfb8aa3b, v20
	v_exp_f32_e32 v20, v20
	s_nop 0
	v_add_f32_e32 v20, 1.0, v20
	v_rcp_f32_e32 v20, v20
	s_nop 0
	v_mul_f32_e32 v20, v20, v21
	v_fmac_f32_e32 v31, v20, v20
	v_cndmask_b32_e64 v54, 0, v20, s[8:9]
	v_mul_f32_e32 v20, 0x3d372713, v38
	v_mul_f32_e32 v20, v20, v38
	v_fma_f32 v20, v20, v38, v38
	v_mul_f32_e32 v20, 0x3fcc422a, v20
	v_mul_f32_e32 v20, 0xbfb8aa3b, v20
	v_exp_f32_e32 v20, v20
	s_nop 0
	v_add_f32_e32 v20, 1.0, v20
	v_rcp_f32_e32 v20, v20
	s_nop 0
	v_mul_f32_e32 v20, v20, v38
	v_fmac_f32_e32 v31, v20, v20
	v_cndmask_b32_e64 v38, 0, v20, s[8:9]
	v_mul_f32_e32 v20, 0x3d372713, v22
	v_mul_f32_e32 v20, v20, v22
	v_fma_f32 v20, v20, v22, v22
	v_mul_f32_e32 v20, 0x3fcc422a, v20
	v_mul_f32_e32 v20, 0xbfb8aa3b, v20
	v_exp_f32_e32 v20, v20
	s_nop 0
	v_add_f32_e32 v20, 1.0, v20
	v_rcp_f32_e32 v20, v20
	s_nop 0
	v_mul_f32_e32 v20, v20, v22
	v_fmac_f32_e32 v31, v20, v20
	v_cndmask_b32_e64 v55, 0, v20, s[8:9]
	v_mul_f32_e32 v20, 0x3d372713, v39
	v_mul_f32_e32 v20, v20, v39
	v_fma_f32 v20, v20, v39, v39
	v_mul_f32_e32 v20, 0x3fcc422a, v20
	v_mul_f32_e32 v20, 0xbfb8aa3b, v20
	v_exp_f32_e32 v20, v20
	s_nop 0
	v_add_f32_e32 v20, 1.0, v20
	v_rcp_f32_e32 v20, v20
	s_nop 0
	v_mul_f32_e32 v20, v20, v39
	v_fmac_f32_e32 v31, v20, v20
	v_cndmask_b32_e64 v39, 0, v20, s[8:9]
	v_mul_f32_e32 v20, 0x3d372713, v23
	v_mul_f32_e32 v20, v20, v23
	v_fma_f32 v20, v20, v23, v23
	v_mul_f32_e32 v20, 0x3fcc422a, v20
	v_mul_f32_e32 v20, 0xbfb8aa3b, v20
	v_exp_f32_e32 v20, v20
	s_nop 0
	v_add_f32_e32 v20, 1.0, v20
	v_rcp_f32_e32 v20, v20
	s_nop 0
	v_mul_f32_e32 v20, v20, v23
	v_fmac_f32_e32 v31, v20, v20
	v_cndmask_b32_e64 v56, 0, v20, s[8:9]
	v_mul_f32_e32 v20, 0x3d372713, v49
	v_mul_f32_e32 v20, v20, v49
	v_fma_f32 v20, v20, v49, v49
	v_mul_f32_e32 v20, 0x3fcc422a, v20
	v_mul_f32_e32 v20, 0xbfb8aa3b, v20
	v_exp_f32_e32 v20, v20
	s_nop 0
	v_add_f32_e32 v20, 1.0, v20
	v_rcp_f32_e32 v20, v20
	s_nop 0
	v_mul_f32_e32 v20, v20, v49
	v_fmac_f32_e32 v31, v20, v20
	v_cndmask_b32_e64 v49, 0, v20, s[8:9]
	v_mul_f32_e32 v20, 0x3d372713, v34
	v_mul_f32_e32 v20, v20, v34
	v_fma_f32 v20, v20, v34, v34
	v_mul_f32_e32 v20, 0x3fcc422a, v20
	v_mul_f32_e32 v20, 0xbfb8aa3b, v20
	v_exp_f32_e32 v20, v20
	s_nop 0
	v_add_f32_e32 v20, 1.0, v20
	v_rcp_f32_e32 v20, v20
	s_nop 0
	v_mul_f32_e32 v20, v20, v34
	v_fmac_f32_e32 v31, v20, v20
	v_cndmask_b32_e64 v57, 0, v20, s[8:9]
	v_mul_f32_e32 v20, 0x3d372713, v50
	v_mul_f32_e32 v20, v20, v50
	v_fma_f32 v20, v20, v50, v50
	v_mul_f32_e32 v20, 0x3fcc422a, v20
	v_mul_f32_e32 v20, 0xbfb8aa3b, v20
	v_exp_f32_e32 v20, v20
	s_nop 0
	v_add_f32_e32 v20, 1.0, v20
	v_rcp_f32_e32 v20, v20
	s_nop 0
	v_mul_f32_e32 v20, v20, v50
	v_fmac_f32_e32 v31, v20, v20
	v_cndmask_b32_e64 v50, 0, v20, s[8:9]
	v_mul_f32_e32 v20, 0x3d372713, v35
	v_mul_f32_e32 v20, v20, v35
	v_fma_f32 v20, v20, v35, v35
	v_mul_f32_e32 v20, 0x3fcc422a, v20
	v_mul_f32_e32 v20, 0xbfb8aa3b, v20
	v_exp_f32_e32 v20, v20
	s_nop 0
	v_add_f32_e32 v20, 1.0, v20
	v_rcp_f32_e32 v20, v20
	s_nop 0
	v_mul_f32_e32 v20, v20, v35
	v_fmac_f32_e32 v31, v20, v20
	v_cndmask_b32_e64 v58, 0, v20, s[8:9]
	v_mul_f32_e32 v20, 0x3d372713, v51
	v_mul_f32_e32 v20, v20, v51
	v_fma_f32 v20, v20, v51, v51
	v_mul_f32_e32 v20, 0x3fcc422a, v20
	v_mul_f32_e32 v20, 0xbfb8aa3b, v20
	v_exp_f32_e32 v20, v20
	s_nop 0
	v_add_f32_e32 v20, 1.0, v20
	v_rcp_f32_e32 v20, v20
	s_nop 0
	v_mul_f32_e32 v20, v20, v51
	v_fmac_f32_e32 v31, v20, v20
	v_cndmask_b32_e64 v51, 0, v20, s[8:9]
	v_mul_f32_e32 v20, 0x3d372713, v36
	v_mul_f32_e32 v20, v20, v36
	v_fma_f32 v20, v20, v36, v36
	v_mul_f32_e32 v20, 0x3fcc422a, v20
	v_mul_f32_e32 v20, 0xbfb8aa3b, v20
	v_exp_f32_e32 v20, v20
	s_nop 0
	v_add_f32_e32 v20, 1.0, v20
	v_rcp_f32_e32 v20, v20
	s_nop 0
	v_mul_f32_e32 v20, v20, v36
	v_fmac_f32_e32 v31, v20, v20
	v_cndmask_b32_e64 v59, 0, v20, s[8:9]
	v_mul_f32_e32 v20, 0x3d372713, v52
	v_mul_f32_e32 v20, v20, v52
	v_fma_f32 v20, v20, v52, v52
	v_mul_f32_e32 v20, 0x3fcc422a, v20
	v_mul_f32_e32 v20, 0xbfb8aa3b, v20
	v_exp_f32_e32 v20, v20
	s_nop 0
	v_add_f32_e32 v20, 1.0, v20
	v_rcp_f32_e32 v20, v20
	s_nop 0
	v_mul_f32_e32 v20, v20, v52
	v_fmac_f32_e32 v31, v20, v20
	v_cndmask_b32_e64 v52, 0, v20, s[8:9]
	v_mul_f32_e32 v20, 0x3d372713, v37
	v_mul_f32_e32 v20, v20, v37
	v_fma_f32 v20, v20, v37, v37
	v_mul_f32_e32 v20, 0x3fcc422a, v20
	v_mul_f32_e32 v20, 0xbfb8aa3b, v20
	v_exp_f32_e32 v20, v20
	s_nop 0
	v_add_f32_e32 v20, 1.0, v20
	v_rcp_f32_e32 v20, v20
	s_nop 0
	v_mul_f32_e32 v20, v20, v37
	v_fmac_f32_e32 v31, v20, v20
	v_cndmask_b32_e64 v60, 0, v20, s[8:9]
	s_waitcnt vmcnt(4)
; __device__ __forceinline__ float bflo(unsigned w) { return __uint_as_float(w << 16); }
; __device__ __forceinline__ float bfhi(unsigned w) { return __uint_as_float(w & 0xffff0000u); }
; __device__ __forceinline__ float gelu_t(float x) { return x * sigm(1.5957691216057308f * (x + 0.044715f * x * x * x)); }
; __device__ __forceinline__ void gmlp_item(const Params& p, int l, int item, LAS unsigned char* lds) {
;     ...
; #pragma unroll
;       for (int i = 0; i < 16; ++i) keep[i] = 0.f;
; #pragma unroll
;       for (int gg = 0; gg < 4; ++gg) { const u32x4 w0 = *(const u32x4*)(vp + gg * 64), w1 = *(const u32x4*)(vp + gg * 64 + 8);
;           const float v[16] = {bflo(w0.x), bfhi(w0.x), bflo(w0.y), bfhi(w0.y), bflo(w0.z), bfhi(w0.z), bflo(w0.w), bfhi(w0.w),
;                                bflo(w1.x), bfhi(w1.x), bflo(w1.y), bfhi(w1.y), bflo(w1.z), bfhi(w1.z), bflo(w1.w), bfhi(w1.w)};
; #pragma unroll
;           for (int i = 0; i < 16; ++i) { const float ge = gelu_t(v[i]); ss += ge * ge; keep[i] = (gg == g) ? ge : keep[i]; } }
	v_mov_b32_e32 v20, v102
	v_mov_b32_e32 v21, v103
	v_mov_b32_e32 v22, v104
	v_mov_b32_e32 v23, v105
	v_mov_b32_e32 v34, v106
	v_mov_b32_e32 v35, v107
	v_mov_b32_e32 v36, v108
	v_mov_b32_e32 v37, v109
	s_cselect_b64 s[8:9], -1, 0
	s_cmp_eq_u32 s37, 2
	v_lshlrev_b32_e32 v65, 16, v20
	v_lshlrev_b32_e32 v61, 16, v34
	v_mul_f32_e32 v69, 0x3d372713, v61
	v_mul_f32_e32 v69, v69, v61
	v_fma_f32 v69, v69, v61, v61
	v_mul_f32_e32 v69, 0x3fcc422a, v69
	v_mul_f32_e32 v69, 0xbfb8aa3b, v69
	v_exp_f32_e32 v69, v69
	v_and_b32_e32 v34, 0xffff0000, v34
	v_lshlrev_b32_e32 v62, 16, v35
	v_and_b32_e32 v35, 0xffff0000, v35
	v_add_f32_e32 v69, 1.0, v69
	v_rcp_f32_e32 v69, v69
	v_lshlrev_b32_e32 v63, 16, v36
	v_and_b32_e32 v36, 0xffff0000, v36
	v_lshlrev_b32_e32 v64, 16, v37
	v_mul_f32_e32 v61, v69, v61
	v_fmac_f32_e32 v31, v61, v61
	v_cndmask_b32_e64 v53, v53, v61, s[8:9]
	v_mul_f32_e32 v61, 0x3d372713, v34
	v_mul_f32_e32 v61, v61, v34
	v_fma_f32 v61, v61, v34, v34
	v_mul_f32_e32 v61, 0x3fcc422a, v61
	v_mul_f32_e32 v61, 0xbfb8aa3b, v61
	v_exp_f32_e32 v61, v61
	v_and_b32_e32 v37, 0xffff0000, v37
	v_and_b32_e32 v20, 0xffff0000, v20
	v_lshlrev_b32_e32 v66, 16, v21
	v_add_f32_e32 v61, 1.0, v61
	v_rcp_f32_e32 v61, v61
	v_and_b32_e32 v21, 0xffff0000, v21
	v_lshlrev_b32_e32 v67, 16, v22
	v_and_b32_e32 v22, 0xffff0000, v22
	v_mul_f32_e32 v34, v61, v34
	v_fmac_f32_e32 v31, v34, v34
	v_cndmask_b32_e64 v26, v26, v34, s[8:9]
	v_mul_f32_e32 v34, 0x3d372713, v62
	v_mul_f32_e32 v34, v34, v62
	v_fma_f32 v34, v34, v62, v62
	v_mul_f32_e32 v34, 0x3fcc422a, v34
	v_mul_f32_e32 v34, 0xbfb8aa3b, v34
	v_exp_f32_e32 v34, v34
	v_lshlrev_b32_e32 v68, 16, v23
	v_and_b32_e32 v23, 0xffff0000, v23
	v_add_f32_e32 v34, 1.0, v34
	v_rcp_f32_e32 v34, v34
	s_nop 0
	v_mul_f32_e32 v34, v34, v62
	v_fmac_f32_e32 v31, v34, v34
	v_cndmask_b32_e64 v27, v27, v34, s[8:9]
	v_mul_f32_e32 v34, 0x3d372713, v35
	v_mul_f32_e32 v34, v34, v35
	v_fma_f32 v34, v34, v35, v35
	v_mul_f32_e32 v34, 0x3fcc422a, v34
	v_mul_f32_e32 v34, 0xbfb8aa3b, v34
	v_exp_f32_e32 v34, v34
	s_nop 0
	v_add_f32_e32 v34, 1.0, v34
	v_rcp_f32_e32 v34, v34
	s_nop 0
	v_mul_f32_e32 v34, v34, v35
	v_fmac_f32_e32 v31, v34, v34
	v_cndmask_b32_e64 v54, v54, v34, s[8:9]
	v_mul_f32_e32 v34, 0x3d372713, v63
	v_mul_f32_e32 v34, v34, v63
	v_fma_f32 v34, v34, v63, v63
	v_mul_f32_e32 v34, 0x3fcc422a, v34
	v_mul_f32_e32 v34, 0xbfb8aa3b, v34
	v_exp_f32_e32 v34, v34
	s_nop 0
	v_add_f32_e32 v34, 1.0, v34
	v_rcp_f32_e32 v34, v34
	s_nop 0
	v_mul_f32_e32 v34, v34, v63
	v_fmac_f32_e32 v31, v34, v34
	v_cndmask_b32_e64 v38, v38, v34, s[8:9]
	v_mul_f32_e32 v34, 0x3d372713, v36
	v_mul_f32_e32 v34, v34, v36
	v_fma_f32 v34, v34, v36, v36
	v_mul_f32_e32 v34, 0x3fcc422a, v34
	v_mul_f32_e32 v34, 0xbfb8aa3b, v34
	v_exp_f32_e32 v34, v34
	s_nop 0
	v_add_f32_e32 v34, 1.0, v34
	v_rcp_f32_e32 v34, v34
	s_nop 0
	v_mul_f32_e32 v34, v34, v36
	v_fmac_f32_e32 v31, v34, v34
	v_cndmask_b32_e64 v61, v55, v34, s[8:9]
	v_mul_f32_e32 v34, 0x3d372713, v64
	v_mul_f32_e32 v34, v34, v64
	v_fma_f32 v34, v34, v64, v64
	v_mul_f32_e32 v34, 0x3fcc422a, v34
	v_mul_f32_e32 v34, 0xbfb8aa3b, v34
	v_exp_f32_e32 v34, v34
	s_nop 0
	v_add_f32_e32 v34, 1.0, v34
	v_rcp_f32_e32 v34, v34
	s_nop 0
	v_mul_f32_e32 v34, v34, v64
	v_fmac_f32_e32 v31, v34, v34
	v_cndmask_b32_e64 v39, v39, v34, s[8:9]
	v_mul_f32_e32 v34, 0x3d372713, v37
	v_mul_f32_e32 v34, v34, v37
	v_fma_f32 v34, v34, v37, v37
	v_mul_f32_e32 v34, 0x3fcc422a, v34
	v_mul_f32_e32 v34, 0xbfb8aa3b, v34
	v_exp_f32_e32 v34, v34
	s_nop 0
	v_add_f32_e32 v34, 1.0, v34
	v_rcp_f32_e32 v34, v34
	s_nop 0
	v_mul_f32_e32 v34, v34, v37
	v_fmac_f32_e32 v31, v34, v34
	v_cndmask_b32_e64 v62, v56, v34, s[8:9]
	v_mul_f32_e32 v34, 0x3d372713, v65
	v_mul_f32_e32 v34, v34, v65
	v_fma_f32 v34, v34, v65, v65
	v_mul_f32_e32 v34, 0x3fcc422a, v34
	v_mul_f32_e32 v34, 0xbfb8aa3b, v34
	v_exp_f32_e32 v34, v34
	s_nop 0
	v_add_f32_e32 v34, 1.0, v34
	v_rcp_f32_e32 v34, v34
	s_nop 0
	v_mul_f32_e32 v34, v34, v65
	v_fmac_f32_e32 v31, v34, v34
	v_cndmask_b32_e64 v49, v49, v34, s[8:9]
	v_mul_f32_e32 v34, 0x3d372713, v20
	v_mul_f32_e32 v34, v34, v20
	v_fma_f32 v34, v34, v20, v20
	v_mul_f32_e32 v34, 0x3fcc422a, v34
	v_mul_f32_e32 v34, 0xbfb8aa3b, v34
	v_exp_f32_e32 v34, v34
	s_nop 0
	v_add_f32_e32 v34, 1.0, v34
	v_rcp_f32_e32 v34, v34
	s_nop 0
	v_mul_f32_e32 v20, v34, v20
	v_fmac_f32_e32 v31, v20, v20
	v_cndmask_b32_e64 v63, v57, v20, s[8:9]
	v_mul_f32_e32 v20, 0x3d372713, v66
	v_mul_f32_e32 v20, v20, v66
	v_fma_f32 v20, v20, v66, v66
	v_mul_f32_e32 v20, 0x3fcc422a, v20
	v_mul_f32_e32 v20, 0xbfb8aa3b, v20
	v_exp_f32_e32 v20, v20
	s_nop 0
	v_add_f32_e32 v20, 1.0, v20
	v_rcp_f32_e32 v20, v20
	s_nop 0
	v_mul_f32_e32 v20, v20, v66
	v_fmac_f32_e32 v31, v20, v20
	v_cndmask_b32_e64 v64, v50, v20, s[8:9]
	v_mul_f32_e32 v20, 0x3d372713, v21
	v_mul_f32_e32 v20, v20, v21
	v_fma_f32 v20, v20, v21, v21
	v_mul_f32_e32 v20, 0x3fcc422a, v20
	v_mul_f32_e32 v20, 0xbfb8aa3b, v20
	v_exp_f32_e32 v20, v20
	s_nop 0
	v_add_f32_e32 v20, 1.0, v20
	v_rcp_f32_e32 v20, v20
	s_nop 0
	v_mul_f32_e32 v20, v20, v21
	v_fmac_f32_e32 v31, v20, v20
	v_cndmask_b32_e64 v65, v58, v20, s[8:9]
	v_mul_f32_e32 v20, 0x3d372713, v67
	v_mul_f32_e32 v20, v20, v67
	v_fma_f32 v20, v20, v67, v67
	v_mul_f32_e32 v20, 0x3fcc422a, v20
	v_mul_f32_e32 v20, 0xbfb8aa3b, v20
	v_exp_f32_e32 v20, v20
	s_nop 0
	v_add_f32_e32 v20, 1.0, v20
	v_rcp_f32_e32 v20, v20
	s_nop 0
	v_mul_f32_e32 v20, v20, v67
	v_fmac_f32_e32 v31, v20, v20
	v_cndmask_b32_e64 v66, v51, v20, s[8:9]
	v_mul_f32_e32 v20, 0x3d372713, v22
	v_mul_f32_e32 v20, v20, v22
	v_fma_f32 v20, v20, v22, v22
	v_mul_f32_e32 v20, 0x3fcc422a, v20
	v_mul_f32_e32 v20, 0xbfb8aa3b, v20
	v_exp_f32_e32 v20, v20
	s_nop 0
	v_add_f32_e32 v20, 1.0, v20
	v_rcp_f32_e32 v20, v20
	s_nop 0
	v_mul_f32_e32 v20, v20, v22
	v_fmac_f32_e32 v31, v20, v20
	v_cndmask_b32_e64 v59, v59, v20, s[8:9]
	v_mul_f32_e32 v20, 0x3d372713, v68
	v_mul_f32_e32 v20, v20, v68
	v_fma_f32 v20, v20, v68, v68
	v_mul_f32_e32 v20, 0x3fcc422a, v20
	v_mul_f32_e32 v20, 0xbfb8aa3b, v20
	v_exp_f32_e32 v20, v20
	s_nop 0
	v_add_f32_e32 v20, 1.0, v20
	v_rcp_f32_e32 v20, v20
	s_nop 0
	v_mul_f32_e32 v20, v20, v68
	v_fmac_f32_e32 v31, v20, v20
	v_cndmask_b32_e64 v67, v52, v20, s[8:9]
	v_mul_f32_e32 v20, 0x3d372713, v23
	v_mul_f32_e32 v20, v20, v23
	v_fma_f32 v20, v20, v23, v23
	v_mul_f32_e32 v20, 0x3fcc422a, v20
	v_mul_f32_e32 v20, 0xbfb8aa3b, v20
	v_exp_f32_e32 v20, v20
	s_nop 0
	v_add_f32_e32 v20, 1.0, v20
	v_rcp_f32_e32 v20, v20
	s_nop 0
	v_mul_f32_e32 v20, v20, v23
	v_fmac_f32_e32 v31, v20, v20
	v_cndmask_b32_e64 v60, v60, v20, s[8:9]
	s_waitcnt vmcnt(2)
; __device__ __forceinline__ float bflo(unsigned w) { return __uint_as_float(w << 16); }
; __device__ __forceinline__ float bfhi(unsigned w) { return __uint_as_float(w & 0xffff0000u); }
; __device__ __forceinline__ float gelu_t(float x) { return x * sigm(1.5957691216057308f * (x + 0.044715f * x * x * x)); }
; __device__ __forceinline__ void gmlp_item(const Params& p, int l, int item, LAS unsigned char* lds) {
;     ...
; #pragma unroll
;       for (int i = 0; i < 16; ++i) keep[i] = 0.f;
; #pragma unroll
;       for (int gg = 0; gg < 4; ++gg) { const u32x4 w0 = *(const u32x4*)(vp + gg * 64), w1 = *(const u32x4*)(vp + gg * 64 + 8);
;           const float v[16] = {bflo(w0.x), bfhi(w0.x), bflo(w0.y), bfhi(w0.y), bflo(w0.z), bfhi(w0.z), bflo(w0.w), bfhi(w0.w),
;                                bflo(w1.x), bfhi(w1.x), bflo(w1.y), bfhi(w1.y), bflo(w1.z), bfhi(w1.z), bflo(w1.w), bfhi(w1.w)};
; #pragma unroll
;           for (int i = 0; i < 16; ++i) { const float ge = gelu_t(v[i]); ss += ge * ge; keep[i] = (gg == g) ? ge : keep[i]; } }
	v_mov_b32_e32 v20, v110
	v_mov_b32_e32 v21, v111
	v_mov_b32_e32 v22, v112
	v_mov_b32_e32 v23, v113
	v_mov_b32_e32 v34, v114
	v_mov_b32_e32 v35, v115
	v_mov_b32_e32 v36, v116
	v_mov_b32_e32 v37, v117
	s_cselect_b64 s[8:9], -1, 0
	s_cmp_eq_u32 s37, 3
	v_lshlrev_b32_e32 v69, 16, v20
	v_lshlrev_b32_e32 v50, 16, v34
	v_mul_f32_e32 v55, 0x3d372713, v50
	v_mul_f32_e32 v55, v55, v50
	v_fma_f32 v55, v55, v50, v50
	v_mul_f32_e32 v55, 0x3fcc422a, v55
	v_mul_f32_e32 v55, 0xbfb8aa3b, v55
	v_exp_f32_e32 v55, v55
	v_and_b32_e32 v34, 0xffff0000, v34
	v_lshlrev_b32_e32 v51, 16, v35
	v_and_b32_e32 v35, 0xffff0000, v35
	v_add_f32_e32 v55, 1.0, v55
	v_rcp_f32_e32 v55, v55
	v_lshlrev_b32_e32 v52, 16, v36
	v_and_b32_e32 v36, 0xffff0000, v36
	v_lshlrev_b32_e32 v68, 16, v37
	v_mul_f32_e32 v50, v55, v50
	v_fmac_f32_e32 v31, v50, v50
	v_cndmask_b32_e64 v58, v53, v50, s[8:9]
	v_mul_f32_e32 v50, 0x3d372713, v34
	v_mul_f32_e32 v50, v50, v34
	v_fma_f32 v50, v50, v34, v34
	v_mul_f32_e32 v50, 0x3fcc422a, v50
	v_mul_f32_e32 v50, 0xbfb8aa3b, v50
	v_exp_f32_e32 v50, v50
	v_and_b32_e32 v37, 0xffff0000, v37
	v_and_b32_e32 v20, 0xffff0000, v20
	v_lshlrev_b32_e32 v70, 16, v21
	v_add_f32_e32 v50, 1.0, v50
	v_rcp_f32_e32 v50, v50
	v_and_b32_e32 v21, 0xffff0000, v21
	v_lshlrev_b32_e32 v71, 16, v22
	v_and_b32_e32 v22, 0xffff0000, v22
	v_mul_f32_e32 v34, v50, v34
	v_cndmask_b32_e64 v57, v26, v34, s[8:9]
	v_mul_f32_e32 v26, 0x3d372713, v51
	v_mul_f32_e32 v26, v26, v51
	v_fma_f32 v26, v26, v51, v51
	v_mul_f32_e32 v26, 0x3fcc422a, v26
	v_mul_f32_e32 v26, 0xbfb8aa3b, v26
	v_exp_f32_e32 v26, v26
	v_fmac_f32_e32 v31, v34, v34
	v_lshlrev_b32_e32 v72, 16, v23
	v_and_b32_e32 v23, 0xffff0000, v23
	v_add_f32_e32 v26, 1.0, v26
	v_rcp_f32_e32 v26, v26
	s_nop 0
	v_mul_f32_e32 v26, v26, v51
	v_fmac_f32_e32 v31, v26, v26
	v_cndmask_b32_e64 v56, v27, v26, s[8:9]
	v_mul_f32_e32 v26, 0x3d372713, v35
	v_mul_f32_e32 v26, v26, v35
	v_fma_f32 v26, v26, v35, v35
	v_mul_f32_e32 v26, 0x3fcc422a, v26
	v_mul_f32_e32 v26, 0xbfb8aa3b, v26
	v_exp_f32_e32 v26, v26
	s_nop 0
	v_add_f32_e32 v26, 1.0, v26
	v_rcp_f32_e32 v26, v26
	s_nop 0
	v_mul_f32_e32 v26, v26, v35
	v_fmac_f32_e32 v31, v26, v26
	v_cndmask_b32_e64 v55, v54, v26, s[8:9]
	v_mul_f32_e32 v26, 0x3d372713, v52
	v_mul_f32_e32 v26, v26, v52
	v_fma_f32 v26, v26, v52, v52
	v_mul_f32_e32 v26, 0x3fcc422a, v26
	v_mul_f32_e32 v26, 0xbfb8aa3b, v26
	v_exp_f32_e32 v26, v26
	s_nop 0
	v_add_f32_e32 v26, 1.0, v26
	v_rcp_f32_e32 v26, v26
	s_nop 0
	v_mul_f32_e32 v26, v26, v52
	v_fmac_f32_e32 v31, v26, v26
	v_cndmask_b32_e64 v54, v38, v26, s[8:9]
	v_mul_f32_e32 v26, 0x3d372713, v36
	v_mul_f32_e32 v26, v26, v36
	v_fma_f32 v26, v26, v36, v36
	v_mul_f32_e32 v26, 0x3fcc422a, v26
	v_mul_f32_e32 v26, 0xbfb8aa3b, v26
	v_exp_f32_e32 v26, v26
	s_nop 0
	v_add_f32_e32 v26, 1.0, v26
	v_rcp_f32_e32 v26, v26
	s_nop 0
	v_mul_f32_e32 v26, v26, v36
	v_fmac_f32_e32 v31, v26, v26
	v_cndmask_b32_e64 v53, v61, v26, s[8:9]
	v_mul_f32_e32 v26, 0x3d372713, v68
	v_mul_f32_e32 v26, v26, v68
	v_fma_f32 v26, v26, v68, v68
	v_mul_f32_e32 v26, 0x3fcc422a, v26
	v_mul_f32_e32 v26, 0xbfb8aa3b, v26
	v_exp_f32_e32 v26, v26
	s_nop 0
	v_add_f32_e32 v26, 1.0, v26
	v_rcp_f32_e32 v26, v26
	s_nop 0
	v_mul_f32_e32 v26, v26, v68
	v_fmac_f32_e32 v31, v26, v26
	v_cndmask_b32_e64 v52, v39, v26, s[8:9]
	v_mul_f32_e32 v26, 0x3d372713, v37
	v_mul_f32_e32 v26, v26, v37
	v_fma_f32 v26, v26, v37, v37
	v_mul_f32_e32 v26, 0x3fcc422a, v26
	v_mul_f32_e32 v26, 0xbfb8aa3b, v26
	v_exp_f32_e32 v26, v26
	s_nop 0
	v_add_f32_e32 v26, 1.0, v26
	v_rcp_f32_e32 v26, v26
	s_nop 0
	v_mul_f32_e32 v26, v26, v37
	v_fmac_f32_e32 v31, v26, v26
	v_cndmask_b32_e64 v51, v62, v26, s[8:9]
	v_mul_f32_e32 v26, 0x3d372713, v69
	v_mul_f32_e32 v26, v26, v69
	v_fma_f32 v26, v26, v69, v69
	v_mul_f32_e32 v26, 0x3fcc422a, v26
	v_mul_f32_e32 v26, 0xbfb8aa3b, v26
	v_exp_f32_e32 v26, v26
	s_nop 0
	v_add_f32_e32 v26, 1.0, v26
	v_rcp_f32_e32 v26, v26
	s_nop 0
	v_mul_f32_e32 v26, v26, v69
	v_fmac_f32_e32 v31, v26, v26
	v_cndmask_b32_e64 v49, v49, v26, s[8:9]
	v_mul_f32_e32 v26, 0x3d372713, v20
	v_mul_f32_e32 v26, v26, v20
	v_fma_f32 v26, v26, v20, v20
	v_mul_f32_e32 v26, 0x3fcc422a, v26
	v_mul_f32_e32 v26, 0xbfb8aa3b, v26
	v_exp_f32_e32 v26, v26
	s_nop 0
	v_add_f32_e32 v26, 1.0, v26
	v_rcp_f32_e32 v26, v26
	s_nop 0
	v_mul_f32_e32 v20, v26, v20
	v_fmac_f32_e32 v31, v20, v20
	v_cndmask_b32_e64 v50, v63, v20, s[8:9]
	v_mul_f32_e32 v20, 0x3d372713, v70
	v_mul_f32_e32 v20, v20, v70
	v_fma_f32 v20, v20, v70, v70
	v_mul_f32_e32 v20, 0x3fcc422a, v20
	v_mul_f32_e32 v20, 0xbfb8aa3b, v20
	v_exp_f32_e32 v20, v20
	s_nop 0
	v_add_f32_e32 v20, 1.0, v20
	v_rcp_f32_e32 v20, v20
	s_nop 0
	v_mul_f32_e32 v20, v20, v70
	v_fmac_f32_e32 v31, v20, v20
	v_cndmask_b32_e64 v38, v64, v20, s[8:9]
	v_mul_f32_e32 v20, 0x3d372713, v21
	v_mul_f32_e32 v20, v20, v21
	v_fma_f32 v20, v20, v21, v21
	v_mul_f32_e32 v20, 0x3fcc422a, v20
	v_mul_f32_e32 v20, 0xbfb8aa3b, v20
	v_exp_f32_e32 v20, v20
	s_nop 0
	v_add_f32_e32 v20, 1.0, v20
	v_rcp_f32_e32 v20, v20
	s_nop 0
	v_mul_f32_e32 v20, v20, v21
	v_fmac_f32_e32 v31, v20, v20
	v_cndmask_b32_e64 v39, v65, v20, s[8:9]
	v_mul_f32_e32 v20, 0x3d372713, v71
	v_mul_f32_e32 v20, v20, v71
	v_fma_f32 v20, v20, v71, v71
	v_mul_f32_e32 v20, 0x3fcc422a, v20
	v_mul_f32_e32 v20, 0xbfb8aa3b, v20
	v_exp_f32_e32 v20, v20
	s_nop 0
	v_add_f32_e32 v20, 1.0, v20
	v_rcp_f32_e32 v20, v20
	s_nop 0
	v_mul_f32_e32 v20, v20, v71
	v_fmac_f32_e32 v31, v20, v20
	v_cndmask_b32_e64 v35, v66, v20, s[8:9]
	v_mul_f32_e32 v20, 0x3d372713, v22
	v_mul_f32_e32 v20, v20, v22
	v_fma_f32 v20, v20, v22, v22
	v_mul_f32_e32 v20, 0x3fcc422a, v20
	v_mul_f32_e32 v20, 0xbfb8aa3b, v20
	v_exp_f32_e32 v20, v20
	s_nop 0
	v_add_f32_e32 v20, 1.0, v20
	v_rcp_f32_e32 v20, v20
	s_nop 0
	v_mul_f32_e32 v20, v20, v22
	v_fmac_f32_e32 v31, v20, v20
	v_cndmask_b32_e64 v37, v59, v20, s[8:9]
	v_mul_f32_e32 v20, 0x3d372713, v72
	v_mul_f32_e32 v20, v20, v72
	v_fma_f32 v20, v20, v72, v72
	v_mul_f32_e32 v20, 0x3fcc422a, v20
	v_mul_f32_e32 v20, 0xbfb8aa3b, v20
	v_exp_f32_e32 v20, v20
	s_nop 0
	v_add_f32_e32 v20, 1.0, v20
	v_rcp_f32_e32 v20, v20
	s_nop 0
	v_mul_f32_e32 v20, v20, v72
	v_fmac_f32_e32 v31, v20, v20
	v_cndmask_b32_e64 v34, v67, v20, s[8:9]
	v_mul_f32_e32 v20, 0x3d372713, v23
	v_mul_f32_e32 v20, v20, v23
	v_fma_f32 v20, v20, v23, v23
	v_mul_f32_e32 v20, 0x3fcc422a, v20
	v_mul_f32_e32 v20, 0xbfb8aa3b, v20
	v_exp_f32_e32 v20, v20
	s_nop 0
	v_add_f32_e32 v20, 1.0, v20
	v_rcp_f32_e32 v20, v20
	s_nop 0
	v_mul_f32_e32 v20, v20, v23
	v_fmac_f32_e32 v31, v20, v20
	v_cndmask_b32_e64 v36, v60, v20, s[8:9]
	s_waitcnt vmcnt(0)
; __device__ __forceinline__ float bflo(unsigned w) { return __uint_as_float(w << 16); }
; __device__ __forceinline__ float bfhi(unsigned w) { return __uint_as_float(w & 0xffff0000u); }
; __device__ __forceinline__ float gelu_t(float x) { return x * sigm(1.5957691216057308f * (x + 0.044715f * x * x * x)); }
; __device__ __forceinline__ void gmlp_item(const Params& p, int l, int item, LAS unsigned char* lds) {
;     ...
; #pragma unroll
;       for (int i = 0; i < 16; ++i) keep[i] = 0.f;
; #pragma unroll
;       for (int gg = 0; gg < 4; ++gg) { const u32x4 w0 = *(const u32x4*)(vp + gg * 64), w1 = *(const u32x4*)(vp + gg * 64 + 8);
;           const float v[16] = {bflo(w0.x), bfhi(w0.x), bflo(w0.y), bfhi(w0.y), bflo(w0.z), bfhi(w0.z), bflo(w0.w), bfhi(w0.w),
;                                bflo(w1.x), bfhi(w1.x), bflo(w1.y), bfhi(w1.y), bflo(w1.z), bfhi(w1.z), bflo(w1.w), bfhi(w1.w)};
; #pragma unroll
;           for (int i = 0; i < 16; ++i) { const float ge = gelu_t(v[i]); ss += ge * ge; keep[i] = (gg == g) ? ge : keep[i]; } }
	v_mov_b32_e32 v20, v118
	v_mov_b32_e32 v21, v119
	v_mov_b32_e32 v22, v120
	v_mov_b32_e32 v23, v121
	s_nop 0
	v_mov_b32_e32 v24, v122
	v_mov_b32_e32 v25, v123
	v_mov_b32_e32 v26, v124
	v_mov_b32_e32 v27, v125
	s_cselect_b64 s[8:9], -1, 0
	s_waitcnt vmcnt(0)
	v_lshlrev_b32_e32 v59, 16, v24
	v_mul_f32_e32 v63, 0x3d372713, v59
	v_mul_f32_e32 v63, v63, v59
	v_fma_f32 v63, v63, v59, v59
	v_mul_f32_e32 v63, 0x3fcc422a, v63
	v_mul_f32_e32 v63, 0xbfb8aa3b, v63
	v_exp_f32_e32 v63, v63
	v_and_b32_e32 v24, 0xffff0000, v24
	v_lshlrev_b32_e32 v60, 16, v25
	v_and_b32_e32 v25, 0xffff0000, v25
	v_add_f32_e32 v63, 1.0, v63
	v_rcp_f32_e32 v63, v63
	v_lshlrev_b32_e32 v61, 16, v26
	v_and_b32_e32 v26, 0xffff0000, v26
	v_lshlrev_b32_e32 v62, 16, v27
	v_mul_f32_e32 v59, v63, v59
	v_fmac_f32_e32 v31, v59, v59
	v_cndmask_b32_e64 v58, v58, v59, s[8:9]
	v_mul_f32_e32 v59, 0x3d372713, v24
	v_mul_f32_e32 v59, v59, v24
	v_fma_f32 v59, v59, v24, v24
	v_mul_f32_e32 v59, 0x3fcc422a, v59
	v_mul_f32_e32 v59, 0xbfb8aa3b, v59
	v_exp_f32_e32 v59, v59
	v_and_b32_e32 v27, 0xffff0000, v27
	v_add_f32_e32 v59, 1.0, v59
	v_rcp_f32_e32 v59, v59
	s_nop 0
	v_mul_f32_e32 v24, v59, v24
	v_fmac_f32_e32 v31, v24, v24
	v_cndmask_b32_e64 v57, v57, v24, s[8:9]
	v_mul_f32_e32 v24, 0x3d372713, v60
	v_mul_f32_e32 v24, v24, v60
	v_fma_f32 v24, v24, v60, v60
	v_mul_f32_e32 v24, 0x3fcc422a, v24
	v_mul_f32_e32 v24, 0xbfb8aa3b, v24
	v_exp_f32_e32 v24, v24
	s_nop 0
	v_add_f32_e32 v24, 1.0, v24
	v_rcp_f32_e32 v24, v24
	s_nop 0
	v_mul_f32_e32 v24, v24, v60
	v_fmac_f32_e32 v31, v24, v24
	v_cndmask_b32_e64 v56, v56, v24, s[8:9]
	v_mul_f32_e32 v24, 0x3d372713, v25
	v_mul_f32_e32 v24, v24, v25
	v_fma_f32 v24, v24, v25, v25
	v_mul_f32_e32 v24, 0x3fcc422a, v24
	v_mul_f32_e32 v24, 0xbfb8aa3b, v24
	v_exp_f32_e32 v24, v24
	s_nop 0
	v_add_f32_e32 v24, 1.0, v24
	v_rcp_f32_e32 v24, v24
	s_nop 0
	v_mul_f32_e32 v24, v24, v25
	v_fmac_f32_e32 v31, v24, v24
	v_cndmask_b32_e64 v55, v55, v24, s[8:9]
	v_mul_f32_e32 v24, 0x3d372713, v61
	v_mul_f32_e32 v24, v24, v61
	v_fma_f32 v24, v24, v61, v61
	v_mul_f32_e32 v24, 0x3fcc422a, v24
	v_mul_f32_e32 v24, 0xbfb8aa3b, v24
	v_exp_f32_e32 v24, v24
	v_lshlrev_b32_e32 v25, 16, v20
	v_add_f32_e32 v24, 1.0, v24
	v_rcp_f32_e32 v24, v24
	s_nop 0
	v_mul_f32_e32 v24, v24, v61
	v_fmac_f32_e32 v31, v24, v24
	v_cndmask_b32_e64 v54, v54, v24, s[8:9]
	v_mul_f32_e32 v24, 0x3d372713, v26
	v_mul_f32_e32 v24, v24, v26
	v_fma_f32 v24, v24, v26, v26
	v_mul_f32_e32 v24, 0x3fcc422a, v24
	v_mul_f32_e32 v24, 0xbfb8aa3b, v24
	v_exp_f32_e32 v24, v24
	s_nop 0
	v_add_f32_e32 v24, 1.0, v24
	v_rcp_f32_e32 v24, v24
	s_nop 0
	v_mul_f32_e32 v24, v24, v26
	v_fmac_f32_e32 v31, v24, v24
	v_cndmask_b32_e64 v53, v53, v24, s[8:9]
	v_mul_f32_e32 v24, 0x3d372713, v62
	v_mul_f32_e32 v24, v24, v62
	v_fma_f32 v24, v24, v62, v62
	v_mul_f32_e32 v24, 0x3fcc422a, v24
	v_mul_f32_e32 v24, 0xbfb8aa3b, v24
	v_exp_f32_e32 v24, v24
	v_mov_b32_e32 v26, v25
	v_add_f32_e32 v24, 1.0, v24
	v_rcp_f32_e32 v24, v24
	s_nop 0
	v_mul_f32_e32 v24, v24, v62
	v_fmac_f32_e32 v31, v24, v24
	v_cndmask_b32_e64 v52, v52, v24, s[8:9]
	v_mul_f32_e32 v24, 0x3d372713, v27
	v_mul_f32_e32 v24, v24, v27
	v_fma_f32 v24, v24, v27, v27
	v_mul_f32_e32 v24, 0x3fcc422a, v24
	v_mul_f32_e32 v24, 0xbfb8aa3b, v24
	v_exp_f32_e32 v24, v24
	s_nop 0
	v_add_f32_e32 v24, 1.0, v24
	v_rcp_f32_e32 v24, v24
	s_nop 0
	v_mul_f32_e32 v24, v24, v27
	v_fmac_f32_e32 v31, v24, v24
	v_cndmask_b32_e64 v51, v51, v24, s[8:9]
	v_and_b32_e32 v24, 0xffff0000, v20
	v_mul_f32_e32 v20, 0x3d372713, v25
	v_mul_f32_e32 v20, v20, v25
	v_fmac_f32_e32 v26, v20, v26
	v_mul_f32_e32 v20, 0x3fcc422a, v26
	v_mul_f32_e32 v20, 0xbfb8aa3b, v20
	v_exp_f32_e32 v20, v20
	v_mov_b32_e32 v26, v24
	v_add_f32_e32 v20, 1.0, v20
	v_rcp_f32_e32 v27, v20
	v_mul_f32_e32 v20, 0x3d372713, v24
	v_mul_f32_e32 v20, v20, v24
	v_fmac_f32_e32 v26, v20, v26
	v_mul_f32_e32 v20, 0x3fcc422a, v26
	v_mul_f32_e32 v20, 0xbfb8aa3b, v20
	v_exp_f32_e32 v20, v20
	s_nop 0
	v_add_f32_e32 v20, 1.0, v20
	v_rcp_f32_e32 v26, v20
	s_nop 0
	v_pk_mul_f32 v[24:25], v[26:27], v[24:25]
	s_nop 0
	v_pk_mul_f32 v[26:27], v[24:25], v[24:25]
	v_cndmask_b32_e64 v49, v49, v25, s[8:9]
	v_add_f32_e32 v20, v27, v31
	v_lshlrev_b32_e32 v25, 16, v21
	v_add_f32_e32 v31, v26, v20
	v_cndmask_b32_e64 v20, v50, v24, s[8:9]
	v_and_b32_e32 v24, 0xffff0000, v21
	v_mul_f32_e32 v21, 0x3d372713, v25
	v_mul_f32_e32 v21, v21, v25
	v_mov_b32_e32 v26, v25
	v_fmac_f32_e32 v26, v21, v26
	v_mul_f32_e32 v21, 0x3fcc422a, v26
	v_mul_f32_e32 v21, 0xbfb8aa3b, v21
	v_exp_f32_e32 v21, v21
	v_mov_b32_e32 v26, v24
	v_add_f32_e32 v21, 1.0, v21
	v_rcp_f32_e32 v27, v21
	v_mul_f32_e32 v21, 0x3d372713, v24
	v_mul_f32_e32 v21, v21, v24
	v_fmac_f32_e32 v26, v21, v26
	v_mul_f32_e32 v21, 0x3fcc422a, v26
	v_mul_f32_e32 v21, 0xbfb8aa3b, v21
	v_exp_f32_e32 v21, v21
	s_nop 0
	v_add_f32_e32 v21, 1.0, v21
	v_rcp_f32_e32 v26, v21
	s_nop 0
	v_pk_mul_f32 v[24:25], v[26:27], v[24:25]
	s_nop 0
	v_pk_mul_f32 v[26:27], v[24:25], v[24:25]
	s_nop 0
	v_add_f32_e32 v21, v27, v31
	v_cndmask_b32_e64 v31, v38, v25, s[8:9]
	v_lshlrev_b32_e32 v25, 16, v22
	v_add_f32_e32 v38, v26, v21
	v_cndmask_b32_e64 v21, v39, v24, s[8:9]
	v_and_b32_e32 v24, 0xffff0000, v22
	v_mul_f32_e32 v22, 0x3d372713, v25
	v_mul_f32_e32 v22, v22, v25
	v_mov_b32_e32 v26, v25
	v_fmac_f32_e32 v26, v22, v26
	v_mul_f32_e32 v22, 0x3fcc422a, v26
	v_mul_f32_e32 v22, 0xbfb8aa3b, v22
	v_exp_f32_e32 v22, v22
	v_mov_b32_e32 v26, v24
	v_add_f32_e32 v22, 1.0, v22
	v_rcp_f32_e32 v27, v22
	v_mul_f32_e32 v22, 0x3d372713, v24
	v_mul_f32_e32 v22, v22, v24
; __device__ __forceinline__ bf16_t f2bf(float f) { return (bf16_t)(pk2(f, 0.f) & 0xffffu); }
; __device__ __forceinline__ void lds_barrier() { asm volatile("s_waitcnt lgkmcnt(0)" ::: "memory"); __builtin_amdgcn_s_barrier(); asm volatile("" ::: "memory"); }
; __device__ __forceinline__ void gmlp_item(const Params& p, int l, int item, LAS unsigned char* lds) {
;     ...
;       ss += __shfl_xor(ss, 1); ss += __shfl_xor(ss, 2);
;       const float rstd = rsqrtf(ss * (1.f / 256.f) + EPS);
;       const float* ng = p.gm_norm_g + l * 256 + g * 64 + qd * 16;
; #pragma unroll
;       for (int i = 0; i < 16; ++i) vnT[(qd * 16 + i) * 136 + pp] = f2bf(keep[i] * rstd * ng[i]);
;     }
;     lds_barrier();
;     { f32x4 acc[4];
; #pragma unroll
;       for (int ct = 0; ct < 4; ++ct) acc[ct] = ZERO4;
; #pragma unroll
;       for (int ks = 0; ks < 4; ++ks) if (ks < nks) {
	v_fmac_f32_e32 v26, v22, v26
	v_mul_f32_e32 v22, 0x3fcc422a, v26
	v_mul_f32_e32 v22, 0xbfb8aa3b, v22
	v_exp_f32_e32 v22, v22
	s_nop 0
	v_add_f32_e32 v22, 1.0, v22
	v_rcp_f32_e32 v26, v22
	s_nop 0
	v_pk_mul_f32 v[24:25], v[26:27], v[24:25]
	s_nop 0
	v_pk_mul_f32 v[26:27], v[24:25], v[24:25]
	v_cndmask_b32_e64 v22, v35, v25, s[8:9]
	v_add_f32_e32 v27, v27, v38
	v_add_f32_e32 v25, v26, v27
	v_lshlrev_b32_e32 v27, 16, v23
	v_and_b32_e32 v26, 0xffff0000, v23
	v_mul_f32_e32 v23, 0x3d372713, v27
	v_mul_f32_e32 v23, v23, v27
	v_mov_b32_e32 v35, v27
	v_fmac_f32_e32 v35, v23, v35
	v_mul_f32_e32 v23, 0x3fcc422a, v35
	v_mul_f32_e32 v23, 0xbfb8aa3b, v23
	v_exp_f32_e32 v23, v23
	v_mov_b32_e32 v35, v26
	v_cndmask_b32_e64 v24, v37, v24, s[8:9]
	v_add_f32_e32 v23, 1.0, v23
	v_rcp_f32_e32 v39, v23
	v_mul_f32_e32 v23, 0x3d372713, v26
	v_mul_f32_e32 v23, v23, v26
	v_fmac_f32_e32 v35, v23, v35
	v_mul_f32_e32 v23, 0x3fcc422a, v35
	v_mul_f32_e32 v23, 0xbfb8aa3b, v23
	v_exp_f32_e32 v23, v23
	s_nop 0
	v_add_f32_e32 v23, 1.0, v23
	v_rcp_f32_e32 v38, v23
	s_nop 0
	v_pk_mul_f32 v[38:39], v[38:39], v[26:27]
	s_nop 0
	v_cndmask_b32_e64 v26, v34, v39, s[8:9]
	v_and_b32_e32 v34, 64, v207
	v_pk_mul_f32 v[60:61], v[38:39], v[38:39]
	v_xor_b32_e32 v27, 1, v207
	v_add_u32_e32 v34, 64, v34
	v_add_f32_e32 v23, v61, v25
	v_cndmask_b32_e64 v25, v36, v38, s[8:9]
	v_cmp_lt_i32_e64 s[8:9], v27, v34
	v_add_f32_e32 v23, v60, v23
	v_mov_b32_e32 v39, 0
	v_cndmask_b32_e64 v27, v207, v27, s[8:9]
	v_lshlrev_b32_e32 v27, 2, v27
	ds_bpermute_b32 v27, v27, v23
	s_waitcnt lgkmcnt(0)
	v_add_f32_e32 v23, v23, v27
	v_xor_b32_e32 v27, 2, v207
	v_cmp_lt_i32_e64 s[8:9], v27, v34
	s_nop 1
	v_cndmask_b32_e64 v27, v207, v27, s[8:9]
	v_lshlrev_b32_e32 v27, 2, v27
	ds_bpermute_b32 v27, v27, v23
	s_waitcnt lgkmcnt(0)
	v_add_f32_e32 v23, v23, v27
	v_fmamk_f32 v23, v23, 0x3b800000, v204
	v_cmp_gt_f32_e64 s[8:9], s93, v23
	v_mul_f32_e32 v27, 0x4b800000, v23
	s_nop 0
	v_cndmask_b32_e64 v23, v23, v27, s[8:9]
	v_rsq_f32_e32 v23, v23
	s_nop 0
	v_mul_f32_e32 v27, 0x45800000, v23
	v_cndmask_b32_e64 v27, v23, v27, s[8:9]
	s_lshl_b64 s[8:9], s[28:29], 2
	s_add_u32 s0, s23, s8
	s_addc_u32 s9, s36, s9
	s_lshl_b32 s8, s37, 8
	s_add_u32 s8, s0, s8
	s_addc_u32 s9, s9, 0
	v_lshlrev_b32_e32 v23, 2, v29
	v_mov_b32_e32 v34, v74
	v_mov_b32_e32 v35, v75
	v_mov_b32_e32 v36, v76
	v_mov_b32_e32 v37, v77
	v_mul_u32_u24_e32 v29, 0x110, v29
	v_add3_u32 v29, 0, v30, v29
	v_mul_f32_e32 v30, v57, v27
	v_mul_f32_e32 v38, v58, v27
	v_mul_f32_e32 v20, v20, v27
	s_movk_i32 s0, 0x110
	s_waitcnt vmcnt(0)
	v_mul_f32_e32 v30, v35, v30
	v_cvt_pk_bf16_f32 v30, v30, v2
	ds_write_b16 v29, v30 offset:272
	v_mul_f32_e32 v30, v56, v27
	v_mul_f32_e32 v30, v36, v30
	v_mul_f32_e32 v34, v34, v38
	v_cvt_pk_bf16_f32 v30, v30, v2
	v_cvt_pk_bf16_f32 v34, v34, v2
	ds_write_b16 v29, v30 offset:544
	v_mul_f32_e32 v30, v55, v27
	ds_write_b16 v29, v34
	v_mul_f32_e32 v30, v37, v30
	v_mov_b32_e32 v34, v78
	v_mov_b32_e32 v35, v79
	v_mov_b32_e32 v36, v80
	v_mov_b32_e32 v37, v81
	v_cvt_pk_bf16_f32 v30, v30, v2
	ds_write_b16 v29, v30 offset:816
	v_mul_f32_e32 v30, v54, v27
	v_mov_b32_e32 v38, 0
	s_waitcnt vmcnt(0)
	v_mul_f32_e32 v30, v34, v30
	v_cvt_pk_bf16_f32 v30, v30, v2
	ds_write_b16 v29, v30 offset:1088
	v_mul_f32_e32 v30, v53, v27
	v_mul_f32_e32 v30, v35, v30
	v_cvt_pk_bf16_f32 v30, v30, v2
	ds_write_b16 v29, v30 offset:1360
	v_mul_f32_e32 v30, v52, v27
	v_mul_f32_e32 v30, v36, v30
	v_cvt_pk_bf16_f32 v30, v30, v2
	ds_write_b16 v29, v30 offset:1632
	v_mul_f32_e32 v30, v51, v27
	v_mul_f32_e32 v30, v37, v30
	v_mov_b32_e32 v34, v82
	v_mov_b32_e32 v35, v83
	v_mov_b32_e32 v36, v84
	v_mov_b32_e32 v37, v85
	v_cvt_pk_bf16_f32 v30, v30, v2
	ds_write_b16 v29, v30 offset:1904
	v_mul_f32_e32 v30, v49, v27
	s_waitcnt vmcnt(0)
	v_mul_f32_e32 v20, v35, v20
	v_cvt_pk_bf16_f32 v20, v20, v2
	ds_write_b16 v29, v20 offset:2448
	v_mul_f32_e32 v20, v31, v27
	v_mul_f32_e32 v20, v36, v20
	v_cvt_pk_bf16_f32 v20, v20, v2
	ds_write_b16 v29, v20 offset:2720
	v_mul_f32_e32 v20, v21, v27
	v_mul_f32_e32 v30, v34, v30
	v_mul_f32_e32 v20, v37, v20
	v_cvt_pk_bf16_f32 v30, v30, v2
	v_cvt_pk_bf16_f32 v20, v20, v2
	ds_write_b16 v29, v30 offset:2176
	ds_write_b16 v29, v20 offset:2992
	v_mul_f32_e32 v30, v22, v27
	v_mov_b32_e32 v20, v86
	v_mov_b32_e32 v21, v87
	v_mov_b32_e32 v22, v88
	v_mov_b32_e32 v23, v89
	v_mov_b32_e32 v36, 0
	v_cmp_lt_i32_e64 s[8:9], -1, v33
	v_mov_b32_e32 v37, 0
	v_mov_b32_e32 v33, v36
	v_mov_b32_e32 v34, v36
	v_mov_b32_e32 v35, v36
	v_mov_b32_e32 v31, v36
	s_waitcnt vmcnt(0)
	v_mul_f32_e32 v20, v20, v30
	v_cvt_pk_bf16_f32 v20, v20, v2
	ds_write_b16 v29, v20 offset:3264
	v_mul_f32_e32 v20, v24, v27
	v_mul_f32_e32 v20, v21, v20
	v_cvt_pk_bf16_f32 v20, v20, v2
	ds_write_b16 v29, v20 offset:3536
	v_mul_f32_e32 v20, v26, v27
	v_mul_f32_e32 v20, v22, v20
	v_cvt_pk_bf16_f32 v20, v20, v2
	ds_write_b16 v29, v20 offset:3808
	v_mul_f32_e32 v20, v25, v27
	v_mul_f32_e32 v20, v23, v20
	v_cvt_pk_bf16_f32 v20, v20, v2
	ds_write_b16 v29, v20 offset:4080
	s_waitcnt lgkmcnt(0)
	s_barrier
	v_add_u32_e32 v20, 0, v28
	v_mad_u32_u24 v49, v32, s0, v20
	v_mov_b32_e32 v32, 0
	v_mov_b32_e32 v28, v36
	v_mov_b32_e32 v29, v36
	v_mov_b32_e32 v30, v36
	v_mov_b32_e32 v24, v36
	v_mov_b32_e32 v25, v36
	v_mov_b32_e32 v26, v36
	v_mov_b32_e32 v27, v36
	v_mov_b32_e32 v20, v36
	v_mov_b32_e32 v21, v36
	v_mov_b32_e32 v22, v36
	v_mov_b32_e32 v23, v36
	s_and_saveexec_b64 s[14:15], s[8:9]
	s_cbranch_execnz .LBB0_344
	s_or_b64 exec, exec, s[14:15]
	s_and_saveexec_b64 s[8:9], s[6:7]
	s_cbranch_execnz .LBB0_345
